# pvprio_s + up GEMM unit order with row-panel group 16 instead of 8
# speedup vs baseline: 1.0007x; 1.0007x over previous
;     __device__ bool next(int i, Unit& u) const {
;         const long L = (long)i * G + c; if (L >= nwg) return false;
;         int wgid = (int)L; { const int q = nwg / NXCD, r = nwg % NXCD, xcd = wgid % NXCD, off = wgid / NXCD; wgid = (xcd < r ? xcd * (q + 1) : r * (q + 1) + (xcd - r) * q) + off; }
;         const int nig = wgm * nN, gid = wgid / nig, fm = gid * wgm, gsz = (nM - fm) < wgm ? (nM - fm) : wgm;
;         u.pm = fm + ((wgid % nig) % gsz); u.pn = (wgid % nig) / gsz; if (rev) u.pm = nM - 1 - u.pm; return true;
; __global__ void __launch_bounds__(NWAVES * 64, 2) fwd_kernel(Args args) {
;     ...
;             { pg8::Unit u; for (int i = wave >> 2; S.next(i, u); i += 2)       { const int row = tid & 255; const int ai = row >> 7, wr = (row >> 6) & 1, m = (row >> 4) & 3, fr = row & 15;
;                 const int pp = UPM * u.pm - 1 + 126 * wr + 8 * fr + 4 * ai + m;
;                 const int tok = min(max(pp - (pp > SEQ ? 1 : 0) - (pp > 2 * SEQ + 1 ? 1 : 0), 0), M - 1);
;                 const float* p = SSX + (size_t)tok * 16;
;                 const f32x4 a = *(const f32x4*)p, b = *(const f32x4*)(p + 4), c = *(const f32x4*)(p + 8), d = *(const f32x4*)(p + 12);
.LBB0_522:
	v_readlane_b32 s12, v255, 2
	v_readlane_b32 s13, v255, 3
	s_xor_b64 s[22:23], s[12:13], -1
	s_xor_b64 s[24:25], s[88:89], -1
	v_readlane_b32 s14, v252, 3
	v_readlane_b32 s15, v252, 4
	s_cmp_le_i32 s14, s5
	s_cselect_b64 s[12:13], -1, 0
	s_cmp_lt_i32 s5, s15
	s_cselect_b64 s[14:15], -1, 0
	s_and_b64 s[34:35], s[12:13], s[14:15]
	s_andn2_b64 vcc, exec, s[34:35]
	s_cbranch_vccnz .LBB0_619
	v_mbcnt_lo_u32_b32 v0, -1, 0
	v_mbcnt_hi_u32_b32 v0, -1, v0
	v_readlane_b32 s0, v252, 43
	v_readlane_b32 s18, v254, 48
	v_readlane_b32 s5, v254, 51
	s_nop 0
	v_add_u32_e32 v0, s0, v0
	v_and_b32_e32 v2, 0xff, v0
	v_bfe_u32 v3, v0, 4, 2
	v_bfe_i32 v4, v0, 6, 1
	v_lshlrev_b32_e32 v5, 3, v0
	v_lshrrev_b32_e32 v0, 5, v0
	v_and_b32_e32 v5, 0x78, v5
	v_and_b32_e32 v0, 4, v0
	v_and_b32_e32 v4, 0x7e, v4
	v_or3_b32 v0, v5, v0, v3
	v_add3_u32 v0, v0, v4, -1
	v_lshl_add_u32 v2, v2, 2, s5
	v_mov_b32_e32 v175, 0xbfff
	s_mov_b32 s10, 0
	s_cmpk_lt_u32 s18, 0x10d8
	s_cbranch_scc0 .Lupre_issued
	s_and_b32 s12, s18, 7
	s_lshr_b32 s13, s18, 3
	s_mulk_i32 s12, 0x21b
	s_add_i32 s12, s12, s13
	s_lshr_b32 s13, s12, 5
	s_mul_hi_u32 s13, s13, 0xba2e8ba3
	s_lshr_b32 s13, s13, 3
	s_mul_i32 s14, s13, 0x160
	s_sub_i32 s12, s12, s14
	s_lshl_b32 s13, s13, 4
	s_sub_i32 s14, 0xc4, s13
	s_min_u32 s14, s14, 16
	s_sub_i32 s14, s14, 1
	s_and_b32 s12, s12, s14
	s_add_i32 s12, s13, s12
	s_mulk_i32 s12, 0xfc
	v_add_u32_e32 v166, s12, v0
	v_cmp_lt_i32_e32 vcc, 0x4000, v166
	s_nop 1
	v_subbrev_co_u32_e32 v3, vcc, 0, v166, vcc
	v_cmp_lt_i32_e32 vcc, 0x8001, v166
	s_nop 1
	v_subbrev_co_u32_e32 v3, vcc, 0, v3, vcc
	v_med3_i32 v3, v3, 0, v175
	v_lshlrev_b32_e32 v3, 6, v3
	global_load_dwordx4 v[22:25], v3, s[28:29] offset:48
	global_load_dwordx4 v[26:29], v3, s[28:29] offset:32
	global_load_dwordx4 v[30:33], v3, s[28:29] offset:16
	global_load_dwordx4 v[34:37], v3, s[28:29]
	s_add_u32 s18, s18, s74
	s_add_i32 s10, s10, 1
	s_cmpk_lt_u32 s18, 0x10d8
	s_cbranch_scc0 .Lupre_issued
	s_and_b32 s12, s18, 7
	s_lshr_b32 s13, s18, 3
	s_mulk_i32 s12, 0x21b
	s_add_i32 s12, s12, s13
	s_lshr_b32 s13, s12, 5
	s_mul_hi_u32 s13, s13, 0xba2e8ba3
	s_lshr_b32 s13, s13, 3
	s_mul_i32 s14, s13, 0x160
	s_sub_i32 s12, s12, s14
	s_lshl_b32 s13, s13, 4
	s_sub_i32 s14, 0xc4, s13
	s_min_u32 s14, s14, 16
	s_sub_i32 s14, s14, 1
	s_and_b32 s12, s12, s14
	s_add_i32 s12, s13, s12
	s_mulk_i32 s12, 0xfc
	v_add_u32_e32 v167, s12, v0
	v_cmp_lt_i32_e32 vcc, 0x4000, v167
	s_nop 1
	v_subbrev_co_u32_e32 v3, vcc, 0, v167, vcc
	v_cmp_lt_i32_e32 vcc, 0x8001, v167
	s_nop 1
	v_subbrev_co_u32_e32 v3, vcc, 0, v3, vcc
	v_med3_i32 v3, v3, 0, v175
	v_lshlrev_b32_e32 v3, 6, v3
	global_load_dwordx4 v[38:41], v3, s[28:29] offset:48
	global_load_dwordx4 v[42:45], v3, s[28:29] offset:32
	global_load_dwordx4 v[46:49], v3, s[28:29] offset:16
	global_load_dwordx4 v[50:53], v3, s[28:29]
	s_add_u32 s18, s18, s74
	s_add_i32 s10, s10, 1
	s_cmpk_lt_u32 s18, 0x10d8
	s_cbranch_scc0 .Lupre_issued
	s_and_b32 s12, s18, 7
	s_lshr_b32 s13, s18, 3
	s_mulk_i32 s12, 0x21b
	s_add_i32 s12, s12, s13
	s_lshr_b32 s13, s12, 5
	s_mul_hi_u32 s13, s13, 0xba2e8ba3
	s_lshr_b32 s13, s13, 3
	s_mul_i32 s14, s13, 0x160
	s_sub_i32 s12, s12, s14
	s_lshl_b32 s13, s13, 4
	s_sub_i32 s14, 0xc4, s13
	s_min_u32 s14, s14, 16
	s_sub_i32 s14, s14, 1
	s_and_b32 s12, s12, s14
	s_add_i32 s12, s13, s12
	s_mulk_i32 s12, 0xfc
	v_add_u32_e32 v168, s12, v0
	v_cmp_lt_i32_e32 vcc, 0x4000, v168
	s_nop 1
	v_subbrev_co_u32_e32 v3, vcc, 0, v168, vcc
	v_cmp_lt_i32_e32 vcc, 0x8001, v168
	s_nop 1
	v_subbrev_co_u32_e32 v3, vcc, 0, v3, vcc
	v_med3_i32 v3, v3, 0, v175
	v_lshlrev_b32_e32 v3, 6, v3
	global_load_dwordx4 v[54:57], v3, s[28:29] offset:48
	global_load_dwordx4 v[58:61], v3, s[28:29] offset:32
	global_load_dwordx4 v[62:65], v3, s[28:29] offset:16
	global_load_dwordx4 v[66:69], v3, s[28:29]
	s_add_u32 s18, s18, s74
	s_add_i32 s10, s10, 1
	s_cmpk_lt_u32 s18, 0x10d8
	s_cbranch_scc0 .Lupre_issued
	s_and_b32 s12, s18, 7
	s_lshr_b32 s13, s18, 3
	s_mulk_i32 s12, 0x21b
	s_add_i32 s12, s12, s13
	s_lshr_b32 s13, s12, 5
	s_mul_hi_u32 s13, s13, 0xba2e8ba3
	s_lshr_b32 s13, s13, 3
	s_mul_i32 s14, s13, 0x160
	s_sub_i32 s12, s12, s14
	s_lshl_b32 s13, s13, 4
	s_sub_i32 s14, 0xc4, s13
	s_min_u32 s14, s14, 16
	s_sub_i32 s14, s14, 1
	s_and_b32 s12, s12, s14
	s_add_i32 s12, s13, s12
	s_mulk_i32 s12, 0xfc
	v_add_u32_e32 v169, s12, v0
	v_cmp_lt_i32_e32 vcc, 0x4000, v169
	s_nop 1
	v_subbrev_co_u32_e32 v3, vcc, 0, v169, vcc
	v_cmp_lt_i32_e32 vcc, 0x8001, v169
	s_nop 1
	v_subbrev_co_u32_e32 v3, vcc, 0, v3, vcc
	v_med3_i32 v3, v3, 0, v175
	v_lshlrev_b32_e32 v3, 6, v3
	global_load_dwordx4 v[70:73], v3, s[28:29] offset:48
	global_load_dwordx4 v[74:77], v3, s[28:29] offset:32
	global_load_dwordx4 v[78:81], v3, s[28:29] offset:16
	global_load_dwordx4 v[82:85], v3, s[28:29]
	s_add_u32 s18, s18, s74
	s_add_i32 s10, s10, 1
	s_cmpk_lt_u32 s18, 0x10d8
	s_cbranch_scc0 .Lupre_issued
;     __device__ bool next(int i, Unit& u) const {
;         const long L = (long)i * G + c; if (L >= nwg) return false;
;         int wgid = (int)L; { const int q = nwg / NXCD, r = nwg % NXCD, xcd = wgid % NXCD, off = wgid / NXCD; wgid = (xcd < r ? xcd * (q + 1) : r * (q + 1) + (xcd - r) * q) + off; }
;         const int nig = wgm * nN, gid = wgid / nig, fm = gid * wgm, gsz = (nM - fm) < wgm ? (nM - fm) : wgm;
;         u.pm = fm + ((wgid % nig) % gsz); u.pn = (wgid % nig) / gsz; if (rev) u.pm = nM - 1 - u.pm; return true;
; __global__ void __launch_bounds__(NWAVES * 64, 2) fwd_kernel(Args args) {
;     ...
;             { pg8::Unit u; for (int i = wave >> 2; S.next(i, u); i += 2)       { const int row = tid & 255; const int ai = row >> 7, wr = (row >> 6) & 1, m = (row >> 4) & 3, fr = row & 15;
;                 const int pp = UPM * u.pm - 1 + 126 * wr + 8 * fr + 4 * ai + m;
;                 const int tok = min(max(pp - (pp > SEQ ? 1 : 0) - (pp > 2 * SEQ + 1 ? 1 : 0), 0), M - 1);
;                 const float* p = SSX + (size_t)tok * 16;
;                 const f32x4 a = *(const f32x4*)p, b = *(const f32x4*)(p + 4), c = *(const f32x4*)(p + 8), d = *(const f32x4*)(p + 12);
	s_and_b32 s12, s18, 7
	s_lshr_b32 s13, s18, 3
	s_mulk_i32 s12, 0x21b
	s_add_i32 s12, s12, s13
	s_lshr_b32 s13, s12, 5
	s_mul_hi_u32 s13, s13, 0xba2e8ba3
	s_lshr_b32 s13, s13, 3
	s_mul_i32 s14, s13, 0x160
	s_sub_i32 s12, s12, s14
	s_lshl_b32 s13, s13, 4
	s_sub_i32 s14, 0xc4, s13
	s_min_u32 s14, s14, 16
	s_sub_i32 s14, s14, 1
	s_and_b32 s12, s12, s14
	s_add_i32 s12, s13, s12
	s_mulk_i32 s12, 0xfc
	v_add_u32_e32 v170, s12, v0
	v_cmp_lt_i32_e32 vcc, 0x4000, v170
	s_nop 1
	v_subbrev_co_u32_e32 v3, vcc, 0, v170, vcc
	v_cmp_lt_i32_e32 vcc, 0x8001, v170
	s_nop 1
	v_subbrev_co_u32_e32 v3, vcc, 0, v3, vcc
	v_med3_i32 v3, v3, 0, v175
	v_lshlrev_b32_e32 v3, 6, v3
	global_load_dwordx4 v[86:89], v3, s[28:29] offset:48
	global_load_dwordx4 v[90:93], v3, s[28:29] offset:32
	global_load_dwordx4 v[94:97], v3, s[28:29] offset:16
	global_load_dwordx4 v[98:101], v3, s[28:29]
	s_add_u32 s18, s18, s74
	s_add_i32 s10, s10, 1
	s_cmpk_lt_u32 s18, 0x10d8
	s_cbranch_scc0 .Lupre_issued
	s_and_b32 s12, s18, 7
	s_lshr_b32 s13, s18, 3
	s_mulk_i32 s12, 0x21b
	s_add_i32 s12, s12, s13
	s_lshr_b32 s13, s12, 5
	s_mul_hi_u32 s13, s13, 0xba2e8ba3
	s_lshr_b32 s13, s13, 3
	s_mul_i32 s14, s13, 0x160
	s_sub_i32 s12, s12, s14
	s_lshl_b32 s13, s13, 4
	s_sub_i32 s14, 0xc4, s13
	s_min_u32 s14, s14, 16
	s_sub_i32 s14, s14, 1
	s_and_b32 s12, s12, s14
	s_add_i32 s12, s13, s12
	s_mulk_i32 s12, 0xfc
	v_add_u32_e32 v171, s12, v0
	v_cmp_lt_i32_e32 vcc, 0x4000, v171
	s_nop 1
	v_subbrev_co_u32_e32 v3, vcc, 0, v171, vcc
	v_cmp_lt_i32_e32 vcc, 0x8001, v171
	s_nop 1
	v_subbrev_co_u32_e32 v3, vcc, 0, v3, vcc
	v_med3_i32 v3, v3, 0, v175
	v_lshlrev_b32_e32 v3, 6, v3
	global_load_dwordx4 v[102:105], v3, s[28:29] offset:48
	global_load_dwordx4 v[106:109], v3, s[28:29] offset:32
	global_load_dwordx4 v[110:113], v3, s[28:29] offset:16
	global_load_dwordx4 v[114:117], v3, s[28:29]
	s_add_u32 s18, s18, s74
	s_add_i32 s10, s10, 1
	s_cmpk_lt_u32 s18, 0x10d8
	s_cbranch_scc0 .Lupre_issued
	s_and_b32 s12, s18, 7
	s_lshr_b32 s13, s18, 3
	s_mulk_i32 s12, 0x21b
	s_add_i32 s12, s12, s13
	s_lshr_b32 s13, s12, 5
	s_mul_hi_u32 s13, s13, 0xba2e8ba3
	s_lshr_b32 s13, s13, 3
	s_mul_i32 s14, s13, 0x160
	s_sub_i32 s12, s12, s14
	s_lshl_b32 s13, s13, 4
	s_sub_i32 s14, 0xc4, s13
	s_min_u32 s14, s14, 16
	s_sub_i32 s14, s14, 1
	s_and_b32 s12, s12, s14
	s_add_i32 s12, s13, s12
	s_mulk_i32 s12, 0xfc
	v_add_u32_e32 v172, s12, v0
	v_cmp_lt_i32_e32 vcc, 0x4000, v172
	s_nop 1
	v_subbrev_co_u32_e32 v3, vcc, 0, v172, vcc
	v_cmp_lt_i32_e32 vcc, 0x8001, v172
	s_nop 1
	v_subbrev_co_u32_e32 v3, vcc, 0, v3, vcc
	v_med3_i32 v3, v3, 0, v175
	v_lshlrev_b32_e32 v3, 6, v3
	global_load_dwordx4 v[118:121], v3, s[28:29] offset:48
	global_load_dwordx4 v[122:125], v3, s[28:29] offset:32
	global_load_dwordx4 v[126:129], v3, s[28:29] offset:16
	global_load_dwordx4 v[130:133], v3, s[28:29]
	s_add_u32 s18, s18, s74
	s_add_i32 s10, s10, 1
	s_cmpk_lt_u32 s18, 0x10d8
	s_cbranch_scc0 .Lupre_issued
	s_and_b32 s12, s18, 7
	s_lshr_b32 s13, s18, 3
	s_mulk_i32 s12, 0x21b
	s_add_i32 s12, s12, s13
	s_lshr_b32 s13, s12, 5
	s_mul_hi_u32 s13, s13, 0xba2e8ba3
	s_lshr_b32 s13, s13, 3
	s_mul_i32 s14, s13, 0x160
	s_sub_i32 s12, s12, s14
	s_lshl_b32 s13, s13, 4
	s_sub_i32 s14, 0xc4, s13
	s_min_u32 s14, s14, 16
	s_sub_i32 s14, s14, 1
	s_and_b32 s12, s12, s14
	s_add_i32 s12, s13, s12
	s_mulk_i32 s12, 0xfc
	v_add_u32_e32 v173, s12, v0
	v_cmp_lt_i32_e32 vcc, 0x4000, v173
	s_nop 1
	v_subbrev_co_u32_e32 v3, vcc, 0, v173, vcc
	v_cmp_lt_i32_e32 vcc, 0x8001, v173
	s_nop 1
	v_subbrev_co_u32_e32 v3, vcc, 0, v3, vcc
	v_med3_i32 v3, v3, 0, v175
	v_lshlrev_b32_e32 v3, 6, v3
	global_load_dwordx4 v[134:137], v3, s[28:29] offset:48
	global_load_dwordx4 v[138:141], v3, s[28:29] offset:32
	global_load_dwordx4 v[142:145], v3, s[28:29] offset:16
	global_load_dwordx4 v[146:149], v3, s[28:29]
	s_add_u32 s18, s18, s74
	s_add_i32 s10, s10, 1
	s_cmpk_lt_u32 s18, 0x10d8
	s_cbranch_scc0 .Lupre_issued
	s_and_b32 s12, s18, 7
	s_lshr_b32 s13, s18, 3
	s_mulk_i32 s12, 0x21b
	s_add_i32 s12, s12, s13
	s_lshr_b32 s13, s12, 5
	s_mul_hi_u32 s13, s13, 0xba2e8ba3
	s_lshr_b32 s13, s13, 3
	s_mul_i32 s14, s13, 0x160
	s_sub_i32 s12, s12, s14
	s_lshl_b32 s13, s13, 4
	s_sub_i32 s14, 0xc4, s13
	s_min_u32 s14, s14, 16
	s_sub_i32 s14, s14, 1
	s_and_b32 s12, s12, s14
	s_add_i32 s12, s13, s12
	s_mulk_i32 s12, 0xfc
	v_add_u32_e32 v174, s12, v0
	v_cmp_lt_i32_e32 vcc, 0x4000, v174
	s_nop 1
	v_subbrev_co_u32_e32 v3, vcc, 0, v174, vcc
	v_cmp_lt_i32_e32 vcc, 0x8001, v174
	s_nop 1
	v_subbrev_co_u32_e32 v3, vcc, 0, v3, vcc
	v_med3_i32 v3, v3, 0, v175
	v_lshlrev_b32_e32 v3, 6, v3
	global_load_dwordx4 v[150:153], v3, s[28:29] offset:48
	global_load_dwordx4 v[154:157], v3, s[28:29] offset:32
	global_load_dwordx4 v[158:161], v3, s[28:29] offset:16
	global_load_dwordx4 v[162:165], v3, s[28:29]
	s_add_u32 s18, s18, s74
	s_add_i32 s10, s10, 1

;     __device__ bool next(int i, Unit& u) const {
;         const long L = (long)i * G + c; if (L >= nwg) return false;
;         int wgid = (int)L; { const int q = nwg / NXCD, r = nwg % NXCD, xcd = wgid % NXCD, off = wgid / NXCD; wgid = (xcd < r ? xcd * (q + 1) : r * (q + 1) + (xcd - r) * q) + off; }
;         const int nig = wgm * nN, gid = wgid / nig, fm = gid * wgm, gsz = (nM - fm) < wgm ? (nM - fm) : wgm;
;         u.pm = fm + ((wgid % nig) % gsz); u.pn = (wgid % nig) / gsz; if (rev) u.pm = nM - 1 - u.pm; return true;
; template <class Epi, bool ALIGN_EPI, bool EARLY_DRAIN = true, class Pre = NoPre>
; __device__ __forceinline__ void gemm_phase(LAS unsigned char* lds, const Gemm g, const StaticOrder& S, const Epi& E, int wv, const Pre& pre = Pre()) {
;     ...
;     if (!S.next(0, cur)) return;
; __global__ void __launch_bounds__(NWAVES * 64, 2) fwd_kernel(Args args) {
;     ...
;             __syncthreads();
.Lupre_done:
.LBB0_537:
	v_readlane_b32 s12, v254, 13
	s_waitcnt lgkmcnt(0)
	s_barrier
	v_mbcnt_lo_u32_b32 v0, -1, 0
	v_mbcnt_hi_u32_b32 v0, -1, v0
	v_readlane_b32 s0, v252, 43
	v_readlane_b32 s13, v254, 14
	s_andn2_b64 vcc, exec, s[12:13]
	v_add_u32_e32 v2, s0, v0
	v_cndmask_b32_e64 v0, 0, 1, s[12:13]
	v_cmp_ne_u32_e64 s[38:39], 1, v0
	v_readfirstlane_b32 s0, v2
	s_cbranch_vccnz .LBB0_539
	v_readlane_b32 s5, v254, 50
	s_mov_b32 s46, s5
	v_readlane_b32 s99, v254, 47
	s_and_b32 s5, s2, 7
	s_lshr_b32 s14, s2, 3
	s_mulk_i32 s5, 0x21b
	s_add_i32 s5, s5, s14
	s_lshr_b32 s14, s5, 5
	s_mul_hi_u32 s14, s14, 0xba2e8ba3
	s_lshr_b32 s14, s14, 3
	s_mul_i32 s15, s14, 352
	s_sub_i32 s5, s5, s15
	s_lshl_b32 s14, s14, 4
	s_sub_i32 s15, 0xc4, s14
	s_min_u32 s15, s15, 16
	s_sub_i32 s101, s15, 1
	s_and_b32 s101, s5, s101
	s_add_i32 s99, s14, s101
	s_ff1_i32_b32 s15, s15
	s_lshr_b32 s46, s5, s15

;     __device__ bool next(int i, Unit& u) const {
;         const long L = (long)i * G + c; if (L >= nwg) return false;
;         int wgid = (int)L; { const int q = nwg / NXCD, r = nwg % NXCD, xcd = wgid % NXCD, off = wgid / NXCD; wgid = (xcd < r ? xcd * (q + 1) : r * (q + 1) + (xcd - r) * q) + off; }
;         const int nig = wgm * nN, gid = wgid / nig, fm = gid * wgm, gsz = (nM - fm) < wgm ? (nM - fm) : wgm;
;         u.pm = fm + ((wgid % nig) % gsz); u.pn = (wgid % nig) / gsz; if (rev) u.pm = nM - 1 - u.pm; return true;
; template <class Epi, bool ALIGN_EPI, bool EARLY_DRAIN = true, class Pre = NoPre>
; __device__ __forceinline__ void gemm_phase(LAS unsigned char* lds, const Gemm g, const StaticOrder& S, const Epi& E, int wv, const Pre& pre = Pre()) {
;     ...
;         const bool has_next = S.next(ui + 1, nxt);
;         const char* nA = has_next ? g.A + (size_t)nxt.pm * g.a_tstep + (size_t)(nxt.pm >> 6) * g.a_pad : cA; const char* nB = has_next ? g.Bt + (size_t)nxt.pn * g.b_tstep : cB;
.LBB0_547:
	s_add_i32 s27, s17, 1
	s_mul_i32 s14, s27, s73
	s_mul_hi_u32 s15, s27, s72
	s_add_i32 s15, s15, s14
	s_mul_i32 s14, s27, s72
	s_add_u32 s38, s14, s2
	s_addc_u32 s39, s15, s3
	v_mov_b64_e32 v[2:3], 0x10d8
	v_cmp_lt_i64_e64 s[40:41], s[38:39], v[2:3]
	v_mov_b64_e32 v[2:3], 0x10d7
	v_cmp_gt_i64_e32 vcc, s[38:39], v[2:3]
	s_cbranch_vccnz .LBB0_549
	s_mov_b32 s101, s38
	s_ashr_i32 s14, s38, 31
	s_lshr_b32 s14, s14, 29
	s_add_i32 s14, s38, s14
	s_ashr_i32 s15, s14, 3
	s_and_b32 s14, s14, -8
	s_sub_i32 s14, s38, s14
	s_cmp_lt_i32 s14, 0
	s_movk_i32 s16, 0x21c
	s_cselect_b32 s16, s16, 0x21b
	s_mul_i32 s14, s14, s16
	s_add_i32 s14, s14, s15
	s_mul_hi_i32 s15, s14, 0x2e8ba2e9
	s_lshr_b32 s16, s15, 31
	s_ashr_i32 s15, s15, 5
	s_add_i32 s15, s15, s16
	s_lshl_b32 s16, s15, 3
	s_sub_i32 s38, 0xc4, s16
	s_min_i32 s38, s38, 8
	s_abs_i32 s39, s38
	v_cvt_f32_u32_e32 v0, s39
	s_sub_i32 s43, 0, s39
	s_mulk_i32 s15, 0xb0
	s_sub_i32 s14, s14, s15
	v_rcp_iflag_f32_e32 v0, v0
	s_abs_i32 s15, s14
	s_xor_b32 s42, s14, s38
	s_ashr_i32 s42, s42, 31
	v_mul_f32_e32 v0, 0x4f7ffffe, v0
	v_cvt_u32_f32_e32 v0, v0
	s_nop 0
	v_readfirstlane_b32 s47, v0
	s_mul_i32 s43, s43, s47
	s_mul_hi_u32 s43, s47, s43
	s_add_i32 s47, s47, s43
	s_mul_hi_u32 s43, s15, s47
	s_mul_i32 s47, s43, s39
	s_sub_i32 s15, s15, s47
	s_add_i32 s50, s43, 1
	s_sub_i32 s47, s15, s39
	s_cmp_ge_u32 s15, s39
	s_cselect_b32 s43, s50, s43
	s_cselect_b32 s15, s47, s15
	s_add_i32 s47, s43, 1
	s_cmp_ge_u32 s15, s39
	s_cselect_b32 s15, s47, s43
	s_xor_b32 s15, s15, s42
	s_sub_i32 s60, s15, s42
	s_mul_i32 s15, s60, s38
	s_sub_i32 s14, s14, s15
	s_add_i32 s16, s16, s14
	s_and_b32 s14, s101, 7
	s_lshr_b32 s15, s101, 3
	s_mulk_i32 s14, 0x21b
	s_add_i32 s14, s14, s15
	s_lshr_b32 s15, s14, 5
	s_mul_hi_u32 s15, s15, 0xba2e8ba3
	s_lshr_b32 s15, s15, 3
	s_mul_i32 s38, s15, 352
	s_sub_i32 s14, s14, s38
	s_lshl_b32 s15, s15, 4
	s_sub_i32 s38, 0xc4, s15
	s_min_u32 s38, s38, 16
	s_sub_i32 s39, s38, 1
	s_and_b32 s39, s14, s39
	s_add_i32 s16, s15, s39
	s_ff1_i32_b32 s38, s38
	s_lshr_b32 s60, s14, s38
